# v26: v22o + GEMM phase prologues issue the K-tile-1 stage loads before waiting for K-tile-0 (vmcnt(2)+barrier moved below the 6 loads as vmcnt(8)), 6 GEMM instances
# baseline (speedup 1.0000x reference)
; #define PG8_STAGE(bufoff, gbase, voff) do { _Pragma("unroll") for (int _i = 0; _i < 2; ++_i) \
;         __builtin_amdgcn_global_load_lds((const unsigned*)((const char*)(gbase) + (voff)[_i]), (LAS unsigned*)(lds + (bufoff) + ldsw + _i * 8192), 16, 0, 0); } while (0)
; #define PG8_WAIT_V(n) asm volatile("s_waitcnt vmcnt(" #n ")" ::: "memory")
; #define PG8_BAR __builtin_amdgcn_s_barrier()
; template <class Epi, bool ALIGN_EPI = true>
; __device__ __forceinline__ void gemm_phase(LAS unsigned char* lds, const Gemm g, const StaticOrder& S, const Epi& E) {
;     ...
;     for (int i = 0; i < 2; ++i) { int R, C; stage_rc(tid * 16 + i * 8192, R, C); const int Rb = Epi::PERM ? ((R & ~31) + perm32(R & 31)) : R;
;         voffA[i] = (unsigned)(R * g.lda + C) * 2u; voffB[i] = (unsigned)(Rb * g.ldb + C) * 2u; }
;     const size_t kstep = (size_t)(BK * 2);
;     const size_t hstepA = (size_t)HALF * g.lda * 2, hstepB = (size_t)HALF * g.ldb * 2;
;     const size_t tstepA = 2 * hstepA, tstepB = 2 * hstepB;
;     const int tsplit = g.tsplit; const size_t ajump = (size_t)g.ajump;
;     const unsigned ldsw = (unsigned)wid * 1024u;
;     const int aoff = lds_byte(wr * 64 + fr, fq * 8), boff = lds_byte(wc * 32 + fr, fq * 8);
;     ...
;     PG8_STAGE(PG8_SB(0, 0), cB, voffB); PG8_STAGE(PG8_SB(0, 1), cB + hstepB, voffB); PG8_STAGE(PG8_SA(0, 0), cA, voffA); PG8_STAGE(PG8_SA(0, 1), cA + hstepA, voffA);
;     if (wr == 1) PG8_BAR;
;     PG8_WAIT_V(2); PG8_BAR;
;     PG8_STAGE(PG8_SB(1, 0), cB + kstep, voffB); PG8_STAGE(PG8_SA(1, 0), cA + kstep, voffA); PG8_STAGE(PG8_SB(1, 1), cB + hstepB + kstep, voffB);
;     PG8_WAIT_V(6); PG8_BAR;
.LBB0_53:
	s_lshl_b32 s10, s10, 5
	s_and_b32 s16, s10, 0x60
	s_mov_b64 s[10:11], 0x80
	s_add_i32 m0, s23, 0x18000
	v_lshl_add_u64 v[6:7], v[6:7], 0, s[10:11]
	s_lshl_b32 s14, s5, 13
	global_load_lds_dwordx4 v[6:7], off
	v_lshl_add_u64 v[4:5], v[4:5], 0, s[10:11]
	s_add_i32 m0, s23, 0x1a000
	s_add_i32 s41, s23, 0x8000
	s_add_i32 s42, s23, 0xa000
	global_load_lds_dwordx4 v[4:5], off
	v_lshl_add_u64 v[0:1], v[0:1], 0, s[10:11]
	s_mov_b32 m0, s41
	s_add_u32 s12, s26, 0x80080
	global_load_lds_dwordx4 v[0:1], off
	v_lshl_add_u64 v[0:1], v[2:3], 0, s[10:11]
	s_mov_b32 m0, s42
	s_addc_u32 s13, s27, 0
	global_load_lds_dwordx4 v[0:1], off
	s_add_i32 m0, s23, 0x1c000
	v_lshl_add_u64 v[0:1], s[12:13], 0, v[170:171]
	global_load_lds_dwordx4 v[0:1], off
	v_lshl_add_u64 v[0:1], s[12:13], 0, v[172:173]
	s_add_i32 m0, s23, 0x1e000
	v_lshlrev_b32_e32 v2, 12, v196
	global_load_lds_dwordx4 v[0:1], off
	v_lshlrev_b32_e32 v1, 2, v177
	v_lshl_or_b32 v0, v177, 6, v185
	v_and_b32_e32 v1, 32, v1
	v_bitop3_b32 v0, v0, s14, v1 bitop3:0xde
	v_lshlrev_b32_e32 v1, 9, v168
	v_and_b32_e32 v1, 0x70000, v1
	v_or3_b32 v1, v169, v1, v2
	v_add_u32_e32 v132, v1, v175
	v_lshlrev_b32_e32 v1, 5, v197
	v_and_b32_e32 v1, 0xf0000, v1
	s_mov_b64 s[14:15], 0x80080
	s_waitcnt vmcnt(8)
	s_barrier
	s_waitcnt vmcnt(6)
	s_cmpk_lt_u32 s4, 0x100
	v_or3_b32 v1, v169, v1, v2
	v_lshl_or_b32 v147, s5, 6, v177
	v_lshl_or_b32 v148, s16, 7, v192
	s_cselect_b64 s[12:13], -1, 0
	v_readlane_b32 s4, v255, 9
	v_lshl_add_u64 v[134:135], v[132:133], 0, s[14:15]
	v_add_u32_e32 v132, v1, v175
	s_add_i32 s45, 0, 0x10000
	s_add_i32 s46, 0, 0x14000
	s_sext_i32_i16 s55, s0
	s_ashr_i32 s43, s4, 31
	s_mov_b32 s44, s4
	v_lshl_add_u64 v[136:137], v[132:133], 0, s[14:15]
	v_mov_b64_e32 v[138:139], 0x900
	v_mov_b64_e32 v[140:141], 0x8ff
	v_add_u32_e32 v149, s45, v148
	v_add_u32_e32 v150, s46, v148
	v_add_u32_e32 v151, 0, v0
	s_lshl_b32 s0, s16, 1
	v_lshlrev_b32_e32 v132, 1, v174
	s_mov_b32 s47, 0x601000
	s_movk_i32 s48, 0x3000
	s_mov_b32 s49, 0x603000
	s_mov_b32 s50, 0x9000
	s_mov_b32 s51, 0x609000
	s_mov_b32 s52, 0x60a000
	s_mov_b32 s53, 0xb000
	v_mov_b32_e32 v152, 0x3e0293ee
	s_mov_b32 s54, s1
	s_barrier
	v_readlane_b32 s5, v255, 10
	s_branch .LBB0_56

; #define PG8_STAGE(bufoff, gbase, voff) do { _Pragma("unroll") for (int _i = 0; _i < 2; ++_i) \
;         __builtin_amdgcn_global_load_lds((const unsigned*)((const char*)(gbase) + (voff)[_i]), (LAS unsigned*)(lds + (bufoff) + ldsw + _i * 8192), 16, 0, 0); } while (0)
; #define PG8_WAIT_V(n) asm volatile("s_waitcnt vmcnt(" #n ")" ::: "memory")
; #define PG8_BAR __builtin_amdgcn_s_barrier()
; template <class Epi, bool ALIGN_EPI = true>
; __device__ __forceinline__ void gemm_phase(LAS unsigned char* lds, const Gemm g, const StaticOrder& S, const Epi& E) {
;     ...
;     for (int i = 0; i < 2; ++i) { int R, C; stage_rc(tid * 16 + i * 8192, R, C); const int Rb = Epi::PERM ? ((R & ~31) + perm32(R & 31)) : R;
;         voffA[i] = (unsigned)(R * g.lda + C) * 2u; voffB[i] = (unsigned)(Rb * g.ldb + C) * 2u; }
;     const size_t kstep = (size_t)(BK * 2);
;     const size_t hstepA = (size_t)HALF * g.lda * 2, hstepB = (size_t)HALF * g.ldb * 2;
;     const size_t tstepA = 2 * hstepA, tstepB = 2 * hstepB;
;     const int tsplit = g.tsplit; const size_t ajump = (size_t)g.ajump;
;     const unsigned ldsw = (unsigned)wid * 1024u;
;     const int aoff = lds_byte(wr * 64 + fr, fq * 8), boff = lds_byte(wc * 32 + fr, fq * 8);
;     ...
;     PG8_STAGE(PG8_SB(0, 0), cB, voffB); PG8_STAGE(PG8_SB(0, 1), cB + hstepB, voffB); PG8_STAGE(PG8_SA(0, 0), cA, voffA); PG8_STAGE(PG8_SA(0, 1), cA + hstepA, voffA);
;     if (wr == 1) PG8_BAR;
;     PG8_WAIT_V(2); PG8_BAR;
;     PG8_STAGE(PG8_SB(1, 0), cB + kstep, voffB); PG8_STAGE(PG8_SA(1, 0), cA + kstep, voffA); PG8_STAGE(PG8_SB(1, 1), cB + hstepB + kstep, voffB);
;     PG8_WAIT_V(6); PG8_BAR;
.LBB0_69:
	s_mov_b64 s[6:7], 0x80
	s_lshl_b32 s5, s5, 5
	s_add_i32 m0, s25, 0x18000
	v_lshl_add_u64 v[6:7], v[6:7], 0, s[6:7]
	s_lshl_b32 s12, s4, 13
	s_and_b32 s13, s5, 0x60
	global_load_lds_dwordx4 v[6:7], off
	v_lshl_add_u64 v[4:5], v[4:5], 0, s[6:7]
	s_add_i32 m0, s25, 0x1a000
	s_add_i32 s46, s25, 0x8000
	s_add_i32 s47, s25, 0xa000
	global_load_lds_dwordx4 v[4:5], off
	v_lshl_add_u64 v[0:1], v[0:1], 0, s[6:7]
	s_mov_b32 m0, s46
	s_add_u32 s10, s28, 0x80080
	global_load_lds_dwordx4 v[0:1], off
	v_lshl_add_u64 v[0:1], v[2:3], 0, s[6:7]
	s_mov_b32 m0, s47
	s_addc_u32 s11, s29, 0
	global_load_lds_dwordx4 v[0:1], off
	s_add_i32 m0, s25, 0x1c000
	v_lshl_add_u64 v[0:1], s[10:11], 0, v[170:171]
	global_load_lds_dwordx4 v[0:1], off
	v_lshl_add_u64 v[0:1], s[10:11], 0, v[172:173]
	s_add_i32 m0, s25, 0x1e000
	v_lshlrev_b32_e32 v3, 12, v196
	global_load_lds_dwordx4 v[0:1], off
	v_lshlrev_b32_e32 v1, 2, v177
	v_lshl_or_b32 v0, v177, 6, v185
	v_and_b32_e32 v1, 32, v1
	v_bitop3_b32 v2, v0, s12, v1 bitop3:0xde
	v_lshlrev_b32_e32 v0, 9, v168
	v_and_b32_e32 v0, 0x70000, v0
	v_or3_b32 v0, v169, v0, v3
	v_lshl_or_b32 v144, s4, 6, v177
	s_mov_b64 s[4:5], 0x80080
	v_add_u32_e32 v0, v0, v175
	v_mov_b32_e32 v1, v171
	v_lshl_add_u64 v[132:133], v[0:1], 0, s[4:5]
	v_lshlrev_b32_e32 v0, 5, v197
	v_and_b32_e32 v0, 0xf0000, v0
	s_waitcnt vmcnt(8)
	s_barrier
	s_waitcnt vmcnt(6)
	s_cmpk_lt_u32 s1, 0x100
	v_or3_b32 v0, v169, v0, v3
	s_sext_i32_i8 s55, s0
	v_lshl_or_b32 v145, s13, 7, v192
	s_cselect_b64 s[10:11], -1, 0
	v_readlane_b32 s0, v255, 9
	v_add_u32_e32 v0, v0, v175
	s_add_i32 s50, 0, 0x10000
	s_add_i32 s51, 0, 0x14000
	s_ashr_i32 s48, s0, 31
	s_mov_b32 s49, s0
	v_or_b32_e32 v147, s13, v174
	v_lshl_add_u64 v[134:135], v[0:1], 0, s[4:5]
	v_mov_b64_e32 v[136:137], 0x600
	v_mov_b64_e32 v[138:139], 0x5ff
	v_add_u32_e32 v148, s50, v145
	v_add_u32_e32 v149, s51, v145
	v_add_u32_e32 v150, 0, v2
	s_mov_b32 s52, 0x120000
	s_mov_b64 s[12:13], 0x140000
	s_mov_b32 s53, 0x140000
	s_mov_b64 s[14:15], 0x160000
	s_mov_b32 s54, 0x160000
	s_barrier
	v_readlane_b32 s1, v255, 10
	s_branch .LBB0_72

; #define PG8_STAGE(bufoff, gbase, voff) do { _Pragma("unroll") for (int _i = 0; _i < 2; ++_i) \
;         __builtin_amdgcn_global_load_lds((const unsigned*)((const char*)(gbase) + (voff)[_i]), (LAS unsigned*)(lds + (bufoff) + ldsw + _i * 8192), 16, 0, 0); } while (0)
; #define PG8_WAIT_V(n) asm volatile("s_waitcnt vmcnt(" #n ")" ::: "memory")
; #define PG8_BAR __builtin_amdgcn_s_barrier()
; template <class Epi, bool ALIGN_EPI = true>
; __device__ __forceinline__ void gemm_phase(LAS unsigned char* lds, const Gemm g, const StaticOrder& S, const Epi& E) {
;     ...
;     for (int i = 0; i < 2; ++i) { int R, C; stage_rc(tid * 16 + i * 8192, R, C); const int Rb = Epi::PERM ? ((R & ~31) + perm32(R & 31)) : R;
;         voffA[i] = (unsigned)(R * g.lda + C) * 2u; voffB[i] = (unsigned)(Rb * g.ldb + C) * 2u; }
;     const size_t kstep = (size_t)(BK * 2);
;     const size_t hstepA = (size_t)HALF * g.lda * 2, hstepB = (size_t)HALF * g.ldb * 2;
;     const size_t tstepA = 2 * hstepA, tstepB = 2 * hstepB;
;     const int tsplit = g.tsplit; const size_t ajump = (size_t)g.ajump;
;     const unsigned ldsw = (unsigned)wid * 1024u;
;     const int aoff = lds_byte(wr * 64 + fr, fq * 8), boff = lds_byte(wc * 32 + fr, fq * 8);
;     ...
;     PG8_STAGE(PG8_SB(0, 0), cB, voffB); PG8_STAGE(PG8_SB(0, 1), cB + hstepB, voffB); PG8_STAGE(PG8_SA(0, 0), cA, voffA); PG8_STAGE(PG8_SA(0, 1), cA + hstepA, voffA);
;     if (wr == 1) PG8_BAR;
;     PG8_WAIT_V(2); PG8_BAR;
;     PG8_STAGE(PG8_SB(1, 0), cB + kstep, voffB); PG8_STAGE(PG8_SA(1, 0), cA + kstep, voffA); PG8_STAGE(PG8_SB(1, 1), cB + hstepB + kstep, voffB);
;     PG8_WAIT_V(6); PG8_BAR;
.LBB0_144:
	s_mov_b64 s[10:11], 0x80
	s_lshl_b32 s5, s5, 5
	s_add_i32 m0, s21, 0x18000
	v_lshl_add_u64 v[6:7], v[6:7], 0, s[10:11]
	s_lshl_b32 s12, s4, 13
	s_and_b32 s5, s5, 0x60
	global_load_lds_dwordx4 v[6:7], off
	v_lshl_add_u64 v[2:3], v[2:3], 0, s[10:11]
	s_add_i32 m0, s21, 0x1a000
	s_add_i32 s49, s21, 0x8000
	s_add_i32 s50, s21, 0xa000
	global_load_lds_dwordx4 v[2:3], off
	v_lshl_add_u64 v[0:1], v[0:1], 0, s[10:11]
	s_mov_b32 m0, s49
	s_add_u32 s6, s22, 0x10080
	global_load_lds_dwordx4 v[0:1], off
	v_lshl_add_u64 v[0:1], v[4:5], 0, s[10:11]
	s_mov_b32 m0, s50
	s_addc_u32 s7, s23, 0
	global_load_lds_dwordx4 v[0:1], off
	s_add_i32 m0, s21, 0x1c000
	v_lshl_add_u64 v[0:1], s[6:7], 0, v[130:131]
	global_load_lds_dwordx4 v[0:1], off
	v_lshl_add_u64 v[0:1], s[6:7], 0, v[128:129]
	s_add_i32 m0, s21, 0x1e000
	s_cmpk_lt_u32 s1, 0x100
	global_load_lds_dwordx4 v[0:1], off
	v_lshlrev_b32_e32 v1, 2, v177
	v_lshl_or_b32 v0, v177, 6, v185
	v_and_b32_e32 v1, 32, v1
	s_waitcnt vmcnt(8)
	s_barrier
	s_waitcnt vmcnt(6)
	s_sext_i32_i8 s55, s0
	v_bitop3_b32 v0, v0, s12, v1 bitop3:0xde
	v_lshl_or_b32 v139, s5, 7, v192
	s_cselect_b64 s[12:13], -1, 0
	v_readlane_b32 s0, v255, 9
	s_add_i32 s53, 0, 0x10000
	s_add_i32 s54, 0, 0x14000
	v_lshl_or_b32 v138, s4, 6, v177
	s_ashr_i32 s51, s0, 31
	s_mov_b32 s52, s0
	v_or_b32_e32 v140, s5, v174
	v_mov_b64_e32 v[132:133], 0x180
	v_mov_b64_e32 v[134:135], 0x17f
	v_add_u32_e32 v141, s53, v139
	v_add_u32_e32 v142, s54, v139
	v_add_u32_e32 v143, 0, v0
	s_barrier
	v_readlane_b32 s1, v255, 10
	s_branch .LBB0_147

; #define PG8_STAGE(bufoff, gbase, voff) do { _Pragma("unroll") for (int _i = 0; _i < 2; ++_i) \
;         __builtin_amdgcn_global_load_lds((const unsigned*)((const char*)(gbase) + (voff)[_i]), (LAS unsigned*)(lds + (bufoff) + ldsw + _i * 8192), 16, 0, 0); } while (0)
; #define PG8_WAIT_V(n) asm volatile("s_waitcnt vmcnt(" #n ")" ::: "memory")
; #define PG8_BAR __builtin_amdgcn_s_barrier()
; template <class Epi, bool ALIGN_EPI = true>
; __device__ __forceinline__ void gemm_phase(LAS unsigned char* lds, const Gemm g, const StaticOrder& S, const Epi& E) {
;     ...
;     for (int i = 0; i < 2; ++i) { int R, C; stage_rc(tid * 16 + i * 8192, R, C); const int Rb = Epi::PERM ? ((R & ~31) + perm32(R & 31)) : R;
;         voffA[i] = (unsigned)(R * g.lda + C) * 2u; voffB[i] = (unsigned)(Rb * g.ldb + C) * 2u; }
;     const size_t kstep = (size_t)(BK * 2);
;     const size_t hstepA = (size_t)HALF * g.lda * 2, hstepB = (size_t)HALF * g.ldb * 2;
;     const size_t tstepA = 2 * hstepA, tstepB = 2 * hstepB;
;     const int tsplit = g.tsplit; const size_t ajump = (size_t)g.ajump;
;     const unsigned ldsw = (unsigned)wid * 1024u;
;     const int aoff = lds_byte(wr * 64 + fr, fq * 8), boff = lds_byte(wc * 32 + fr, fq * 8);
;     ...
;     PG8_STAGE(PG8_SB(0, 0), cB, voffB); PG8_STAGE(PG8_SB(0, 1), cB + hstepB, voffB); PG8_STAGE(PG8_SA(0, 0), cA, voffA); PG8_STAGE(PG8_SA(0, 1), cA + hstepA, voffA);
;     if (wr == 1) PG8_BAR;
;     PG8_WAIT_V(2); PG8_BAR;
;     PG8_STAGE(PG8_SB(1, 0), cB + kstep, voffB); PG8_STAGE(PG8_SA(1, 0), cA + kstep, voffA); PG8_STAGE(PG8_SB(1, 1), cB + hstepB + kstep, voffB);
;     PG8_WAIT_V(6); PG8_BAR;
.LBB0_688:
	s_mov_b64 s[12:13], 0x80
	s_lshl_b32 s6, s6, 5
	s_add_i32 m0, s25, 0x18000
	v_lshl_add_u64 v[6:7], v[6:7], 0, s[12:13]
	s_lshl_b32 s8, s1, 13
	s_and_b32 s9, s6, 0x60
	global_load_lds_dwordx4 v[6:7], off
	v_lshl_add_u64 v[4:5], v[4:5], 0, s[12:13]
	s_add_i32 m0, s25, 0x1a000
	s_add_i32 s40, s25, 0x8000
	s_add_i32 s41, s25, 0xa000
	global_load_lds_dwordx4 v[4:5], off
	v_lshl_add_u64 v[2:3], v[2:3], 0, s[12:13]
	s_mov_b32 m0, s40
	s_add_u32 s6, s28, 0xc0080
	global_load_lds_dwordx4 v[2:3], off
	v_lshl_add_u64 v[0:1], v[0:1], 0, s[12:13]
	s_mov_b32 m0, s41
	s_addc_u32 s7, s29, 0
	global_load_lds_dwordx4 v[0:1], off
	s_add_i32 m0, s25, 0x1c000
	v_lshl_add_u64 v[0:1], s[6:7], 0, v[144:145]
	global_load_lds_dwordx4 v[0:1], off
	v_lshl_add_u64 v[0:1], s[6:7], 0, v[146:147]
	s_add_i32 m0, s25, 0x1e000
	v_lshlrev_b32_e32 v2, 13, v196
	global_load_lds_dwordx4 v[0:1], off
	v_lshlrev_b32_e32 v1, 2, v177
	v_lshl_or_b32 v0, v177, 6, v185
	v_and_b32_e32 v1, 32, v1
	v_bitop3_b32 v0, v0, s8, v1 bitop3:0xde
	v_lshlrev_b32_e32 v1, 10, v168
	v_and_b32_e32 v1, 0xe0000, v1
	v_or3_b32 v1, v169, v1, v2
	v_lshl_or_b32 v161, s1, 6, v177
	s_cmpk_lt_u32 s0, 0x100
	v_readlane_b32 s0, v255, 9
	v_add_u32_e32 v148, v1, v175
	v_lshlrev_b32_e32 v1, 6, v197
	s_cselect_b64 s[14:15], -1, 0
	v_readlane_b32 s1, v255, 10
	s_ashr_i32 s42, s0, 31
	s_mov_b32 s43, s0
	v_readlane_b32 s0, v255, 13
	v_and_b32_e32 v1, 0x1e0000, v1
	s_waitcnt vmcnt(8)
	s_barrier
	s_waitcnt vmcnt(6)
	s_ashr_i32 s44, s0, 31
	s_mov_b64 s[0:1], 0x100080
	v_or3_b32 v1, v169, v1, v2
	v_lshl_or_b32 v173, s9, 7, v192
	v_lshl_add_u64 v[150:151], v[148:149], 0, s[0:1]
	v_add_u32_e32 v148, v1, v175
	s_add_i32 s46, 0, 0x10000
	s_add_i32 s47, 0, 0x14000
	v_or_b32_e32 v182, s9, v174
	v_lshl_add_u64 v[152:153], v[148:149], 0, s[0:1]
	v_mov_b64_e32 v[154:155], 0x300
	v_mov_b64_e32 v[156:157], 0x2ff
	s_movk_i32 s45, 0x61
	v_add_u32_e32 v183, s46, v173
	v_add_u32_e32 v186, s47, v173
	v_add_u32_e32 v187, 0, v0
	s_movk_i32 s48, 0x1fff
	s_movk_i32 s49, 0x3000
	s_mov_b32 s16, 0x3fb504f3
	s_barrier
	s_branch .LBB0_691

; #define PG8_STAGE(bufoff, gbase, voff) do { _Pragma("unroll") for (int _i = 0; _i < 2; ++_i) \
;         __builtin_amdgcn_global_load_lds((const unsigned*)((const char*)(gbase) + (voff)[_i]), (LAS unsigned*)(lds + (bufoff) + ldsw + _i * 8192), 16, 0, 0); } while (0)
; #define PG8_WAIT_V(n) asm volatile("s_waitcnt vmcnt(" #n ")" ::: "memory")
; #define PG8_BAR __builtin_amdgcn_s_barrier()
; template <class Epi, bool ALIGN_EPI = true>
; __device__ __forceinline__ void gemm_phase(LAS unsigned char* lds, const Gemm g, const StaticOrder& S, const Epi& E) {
;     ...
;     for (int i = 0; i < 2; ++i) { int R, C; stage_rc(tid * 16 + i * 8192, R, C); const int Rb = Epi::PERM ? ((R & ~31) + perm32(R & 31)) : R;
;         voffA[i] = (unsigned)(R * g.lda + C) * 2u; voffB[i] = (unsigned)(Rb * g.ldb + C) * 2u; }
;     const size_t kstep = (size_t)(BK * 2);
;     const size_t hstepA = (size_t)HALF * g.lda * 2, hstepB = (size_t)HALF * g.ldb * 2;
;     const size_t tstepA = 2 * hstepA, tstepB = 2 * hstepB;
;     const int tsplit = g.tsplit; const size_t ajump = (size_t)g.ajump;
;     const unsigned ldsw = (unsigned)wid * 1024u;
;     const int aoff = lds_byte(wr * 64 + fr, fq * 8), boff = lds_byte(wc * 32 + fr, fq * 8);
;     ...
;     PG8_STAGE(PG8_SB(0, 0), cB, voffB); PG8_STAGE(PG8_SB(0, 1), cB + hstepB, voffB); PG8_STAGE(PG8_SA(0, 0), cA, voffA); PG8_STAGE(PG8_SA(0, 1), cA + hstepA, voffA);
;     if (wr == 1) PG8_BAR;
;     PG8_WAIT_V(2); PG8_BAR;
;     PG8_STAGE(PG8_SB(1, 0), cB + kstep, voffB); PG8_STAGE(PG8_SA(1, 0), cA + kstep, voffA); PG8_STAGE(PG8_SB(1, 1), cB + hstepB + kstep, voffB);
;     PG8_WAIT_V(6); PG8_BAR;
.LBB0_835:
	s_mov_b64 s[8:9], 0x80
	s_lshl_b32 s4, s4, 5
	s_add_i32 m0, s25, 0x18000
	v_lshl_add_u64 v[6:7], v[6:7], 0, s[8:9]
	s_lshl_b32 s6, s1, 13
	s_and_b32 s7, s4, 0x60
	global_load_lds_dwordx4 v[6:7], off
	v_lshl_add_u64 v[4:5], v[4:5], 0, s[8:9]
	s_add_i32 m0, s25, 0x1a000
	s_add_i32 s41, s25, 0x8000
	s_add_i32 s42, s25, 0xa000
	global_load_lds_dwordx4 v[4:5], off
	v_lshl_add_u64 v[0:1], v[0:1], 0, s[8:9]
	s_mov_b32 m0, s41
	s_add_u32 s4, s28, 0x80080
	global_load_lds_dwordx4 v[0:1], off
	v_lshl_add_u64 v[0:1], v[2:3], 0, s[8:9]
	s_mov_b32 m0, s42
	s_addc_u32 s5, s29, 0
	global_load_lds_dwordx4 v[0:1], off
	s_add_i32 m0, s25, 0x1c000
	v_lshl_add_u64 v[0:1], s[4:5], 0, v[170:171]
	global_load_lds_dwordx4 v[0:1], off
	v_lshl_add_u64 v[0:1], s[4:5], 0, v[172:173]
	s_add_i32 m0, s25, 0x1e000
	v_lshl_or_b32 v145, s1, 6, v177
	global_load_lds_dwordx4 v[0:1], off
	v_lshlrev_b32_e32 v1, 2, v177
	s_cmpk_lt_u32 s0, 0x100
	v_readlane_b32 s0, v255, 9
	v_lshl_or_b32 v0, v177, 6, v185
	v_and_b32_e32 v1, 32, v1
	s_cselect_b64 s[16:17], -1, 0
	v_readlane_b32 s1, v255, 10
	s_ashr_i32 s43, s0, 31
	s_mov_b32 s44, s0
	v_readlane_b32 s0, v255, 13
	v_bitop3_b32 v2, v0, s6, v1 bitop3:0xde
	s_waitcnt vmcnt(8)
	s_barrier
	s_waitcnt vmcnt(6)
	s_ashr_i32 s45, s0, 31
	v_add3_u32 v0, v144, v169, v175
	v_mov_b32_e32 v1, v171
	s_mov_b64 s[0:1], 0x180080
	v_lshl_or_b32 v147, s7, 7, v192
	s_waitcnt vmcnt(0)
	v_lshl_add_u64 v[128:129], v[0:1], 0, s[0:1]
	v_add3_u32 v0, v146, v169, v175
	s_add_i32 s47, 0, 0x10000
	s_add_i32 s48, 0, 0x14000
	v_or_b32_e32 v148, s7, v174
	v_lshl_add_u64 v[130:131], v[0:1], 0, s[0:1]
	v_mov_b64_e32 v[132:133], 0xc00
	v_mov_b64_e32 v[134:135], 0xbff
	s_movk_i32 s46, 0x181
	v_add_u32_e32 v149, s47, v147
	v_add_u32_e32 v150, s48, v147
	v_add_u32_e32 v151, 0, v2
	s_barrier
	s_branch .LBB0_838

; #define PG8_STAGE(bufoff, gbase, voff) do { _Pragma("unroll") for (int _i = 0; _i < 2; ++_i) \
;         __builtin_amdgcn_global_load_lds((const unsigned*)((const char*)(gbase) + (voff)[_i]), (LAS unsigned*)(lds + (bufoff) + ldsw + _i * 8192), 16, 0, 0); } while (0)
; #define PG8_WAIT_V(n) asm volatile("s_waitcnt vmcnt(" #n ")" ::: "memory")
; #define PG8_BAR __builtin_amdgcn_s_barrier()
; template <class Epi, bool ALIGN_EPI = true>
; __device__ __forceinline__ void gemm_phase(LAS unsigned char* lds, const Gemm g, const StaticOrder& S, const Epi& E) {
;     ...
;     for (int i = 0; i < 2; ++i) { int R, C; stage_rc(tid * 16 + i * 8192, R, C); const int Rb = Epi::PERM ? ((R & ~31) + perm32(R & 31)) : R;
;         voffA[i] = (unsigned)(R * g.lda + C) * 2u; voffB[i] = (unsigned)(Rb * g.ldb + C) * 2u; }
;     const size_t kstep = (size_t)(BK * 2);
;     const size_t hstepA = (size_t)HALF * g.lda * 2, hstepB = (size_t)HALF * g.ldb * 2;
;     const size_t tstepA = 2 * hstepA, tstepB = 2 * hstepB;
;     const int tsplit = g.tsplit; const size_t ajump = (size_t)g.ajump;
;     const unsigned ldsw = (unsigned)wid * 1024u;
;     const int aoff = lds_byte(wr * 64 + fr, fq * 8), boff = lds_byte(wc * 32 + fr, fq * 8);
;     ...
;     PG8_STAGE(PG8_SB(0, 0), cB, voffB); PG8_STAGE(PG8_SB(0, 1), cB + hstepB, voffB); PG8_STAGE(PG8_SA(0, 0), cA, voffA); PG8_STAGE(PG8_SA(0, 1), cA + hstepA, voffA);
;     if (wr == 1) PG8_BAR;
;     PG8_WAIT_V(2); PG8_BAR;
;     PG8_STAGE(PG8_SB(1, 0), cB + kstep, voffB); PG8_STAGE(PG8_SA(1, 0), cA + kstep, voffA); PG8_STAGE(PG8_SB(1, 1), cB + hstepB + kstep, voffB);
;     PG8_WAIT_V(6); PG8_BAR;
.LBB0_980:
	s_add_u32 s2, s94, 0x1000
	s_addc_u32 s3, s95, 0
	s_lshl_b32 s7, s7, 5
	s_lshl_b32 s18, s6, 13
	s_and_b32 s7, s7, 0x60
	s_add_u32 s8, s94, 0x1e280000
	s_mov_b64 s[10:11], 0x80
	s_addc_u32 s9, s95, 0
	s_add_i32 m0, s38, 0x18000
	v_lshl_add_u64 v[6:7], v[6:7], 0, s[10:11]
	global_load_lds_dwordx4 v[6:7], off
	v_lshl_add_u64 v[4:5], v[4:5], 0, s[10:11]
	s_add_i32 m0, s38, 0x1a000
	s_add_i32 s43, s38, 0x8000
	s_add_i32 s44, s38, 0xa000
	global_load_lds_dwordx4 v[4:5], off
	v_lshl_add_u64 v[0:1], v[0:1], 0, s[10:11]
	s_mov_b32 m0, s43
	s_add_u32 s16, s28, 0x80080
	global_load_lds_dwordx4 v[0:1], off
	v_lshl_add_u64 v[0:1], v[2:3], 0, s[10:11]
	s_mov_b32 m0, s44
	s_addc_u32 s17, s29, 0
	global_load_lds_dwordx4 v[0:1], off
	s_add_i32 m0, s38, 0x1c000
	v_lshl_add_u64 v[0:1], s[16:17], 0, v[170:171]
	global_load_lds_dwordx4 v[0:1], off
	v_lshl_add_u64 v[0:1], s[16:17], 0, v[172:173]
	s_add_i32 m0, s38, 0x1e000
	s_sext_i32_i8 s55, s4
	global_load_lds_dwordx4 v[0:1], off
	v_lshlrev_b32_e32 v1, 2, v177
	s_cmpk_lt_u32 s5, 0x100
	v_readlane_b32 s4, v255, 9
	v_lshl_or_b32 v0, v177, 6, v185
	v_and_b32_e32 v1, 32, v1
	v_readlane_b32 s5, v255, 10
	v_bitop3_b32 v2, v0, s18, v1 bitop3:0xde
	s_waitcnt vmcnt(8)
	s_barrier
	s_waitcnt vmcnt(6)
	s_cselect_b64 s[16:17], -1, 0
	s_ashr_i32 s45, s4, 31
	s_mov_b32 s46, s4
	v_add3_u32 v0, v144, v169, v175
	v_mov_b32_e32 v1, v171
	s_mov_b64 s[4:5], 0x180080
	v_lshl_or_b32 v211, s7, 7, v192
	v_lshl_add_u64 v[144:145], v[0:1], 0, s[4:5]
	v_add3_u32 v0, v146, v169, v175
	s_add_i32 s47, 0, 0x10000
	s_add_i32 s48, 0, 0x14000
	v_lshl_or_b32 v210, s6, 6, v177
	v_or_b32_e32 v212, s7, v174
	v_lshl_add_u64 v[146:147], v[0:1], 0, s[4:5]
	v_mov_b64_e32 v[148:149], 0x300
	v_mov_b64_e32 v[150:151], 0x2ff
	v_add_u32_e32 v213, s47, v211
	v_add_u32_e32 v214, s48, v211
	v_add_u32_e32 v215, 0, v2
	s_mov_b32 s18, 0x3fb504f3
	s_movk_i32 s49, 0x3000
	s_barrier
	s_branch .LBB0_983
